# OUTPROJ converted: 128x256 DMA-staged 16x16x32 loop, K-blocked w_out, register epilogue (x += attn_out, bf16, partial ssq)
# speedup vs baseline: 1.0343x; 1.0116x over previous
; DI void st8(u16* dst, const float (&v)[8]) { *(u32x4*)dst = pack8(v); }
; DI void prep_tile(const float* __restrict__ W, int K, int N, const float* __restrict__ gain, u16* __restrict__ dst, int mode, int tile, char* smem) {
;     ...
;       st8(dst + (size_t)colmap(mode, n) * K + k0 + kc * 8, v);
;     }
;   }
; }
; DI void phase_prep(const Params& p, char* smem) {
;   u16* ws16 = (u16*)p.ws;
;   for (int e = 0; e < 20; ++e) {
;     const int l = e / 10, k = e % 10;
;     const float* W; const float* gain = nullptr; u16* dst; int K, N, mode = 0;
;     switch (k) {
;       case 0: W = p.w_in + (size_t)l * 1024 * DIN; K = 1024; N = DIN; gain = p.mix_norm + l * 1024; dst = (u16*)(p.ws + OFF_WIN + l * SZ_WIN); mode = 1; break;
;       case 1: W = p.w_mla_q_b + (size_t)l * 384 * 768; K = 384; N = 768; gain = p.mla_q_a_norm + l * 384; dst = (u16*)(p.ws + OFF_WQB + l * SZ_WQB); mode = 2; break;
;       case 2: W = p.w_mla_kv_b + (size_t)l * 256 * 1024; K = 256; N = 1024; gain = p.mla_kv_a_norm + l * 256; dst = (u16*)(p.ws + OFF_WKVB + l * SZ_WKVB); break;
;       case 3: W = p.w_mem_kv + (size_t)l * 1024 * 1024; K = 1024; N = 1024; gain = p.mem_norm + l * 1024; dst = (u16*)(p.ws + OFF_WMEM + l * SZ_WMEM); break;
;       case 4: case 5: case 6: W = p.w_branch + (size_t)(l * 3 + (k - 4)) * 512 * 1024; K = 512; N = 1024; dst = (u16*)(p.ws + OFF_WBR + (l * 3 + (k - 4)) * SZ_WBR); break;
;       case 7: W = p.w_out + (size_t)l * 1024 * 1024; K = 1024; N = 1024; dst = (u16*)(p.ws + OFF_WOUT + l * SZ_WOUT); break;
;       case 8: W = p.w_ff1 + (size_t)l * 1024 * 4096; K = 1024; N = 4096; gain = p.ffn_norm + l * 1024; dst = (u16*)(p.ws + OFF_WFF1 + l * SZ_WFF1); break;
;       default: W = p.w_ff2 + (size_t)l * 4096 * 1024; K = 4096; N = 1024; dst = (u16*)(p.ws + OFF_WFF2 + l * SZ_WFF2); break;
;     }
.LBB1_41:
	s_mov_b32 s40, 0
	s_cmp_eq_u32 s73, 7
	s_cselect_b32 s40, 0x10000, s40
	s_cmp_eq_u32 s73, 8
	s_cselect_b32 s40, 0x40000, s40
	s_cmp_eq_u32 s73, 9
	s_cselect_b32 s40, 0x10000, s40
	s_cmp_eq_u32 s73, 17
	s_cselect_b32 s40, 0x10000, s40
	s_cmp_eq_u32 s73, 18
	s_cselect_b32 s40, 0x40000, s40
	s_cmp_eq_u32 s73, 19
	s_cselect_b32 s40, 0x10000, s40
	s_cmp_eq_u32 s73, 0
	s_cbranch_scc1 .Lprep_win2
	s_cmp_eq_u32 s73, 10
	s_cbranch_scc1 .Lprep_win2
	s_cmp_eq_u32 s40, 0
	s_cbranch_scc0 .Lprep_blk2
	v_ashrrev_i32_e32 v16, 31, v14
	v_mad_u64_u32 v[14:15], s[40:41], v14, s74, 0
	v_mov_b32_e32 v2, v15
	v_mad_u64_u32 v[16:17], s[40:41], v16, s74, v[2:3]
	v_mov_b32_e32 v15, v16
	v_lshl_add_u64 v[14:15], v[14:15], 1, v[4:5]
	s_branch .Lprep_st2

; DI void st8(u16* dst, const float (&v)[8]) { *(u32x4*)dst = pack8(v); }
; DI void prep_tile(const float* __restrict__ W, int K, int N, const float* __restrict__ gain, u16* __restrict__ dst, int mode, int tile, char* smem) {
;     ...
;     const int cid = tid + 256 * i, nl = cid >> 3, kc = cid & 7, n = n0 + nl;
;     if (n < N) {
;       float v[8];
; #pragma unroll
;       for (int j = 0; j < 8; ++j) v[j] = Ts[nl * 65 + kc * 8 + j];
;       st8(dst + (size_t)colmap(mode, n) * K + k0 + kc * 8, v);
;     }
;   }
; }
; DI void phase_prep(const Params& p, char* smem) {
;   u16* ws16 = (u16*)p.ws;
;   for (int e = 0; e < 20; ++e) {
;     const int l = e / 10, k = e % 10;
;     const float* W; const float* gain = nullptr; u16* dst; int K, N, mode = 0;
;     switch (k) {
;       case 0: W = p.w_in + (size_t)l * 1024 * DIN; K = 1024; N = DIN; gain = p.mix_norm + l * 1024; dst = (u16*)(p.ws + OFF_WIN + l * SZ_WIN); mode = 1; break;
;       case 1: W = p.w_mla_q_b + (size_t)l * 384 * 768; K = 384; N = 768; gain = p.mla_q_a_norm + l * 384; dst = (u16*)(p.ws + OFF_WQB + l * SZ_WQB); mode = 2; break;
;       case 2: W = p.w_mla_kv_b + (size_t)l * 256 * 1024; K = 256; N = 1024; gain = p.mla_kv_a_norm + l * 256; dst = (u16*)(p.ws + OFF_WKVB + l * SZ_WKVB); break;
;       case 3: W = p.w_mem_kv + (size_t)l * 1024 * 1024; K = 1024; N = 1024; gain = p.mem_norm + l * 1024; dst = (u16*)(p.ws + OFF_WMEM + l * SZ_WMEM); break;
;       case 4: case 5: case 6: W = p.w_branch + (size_t)(l * 3 + (k - 4)) * 512 * 1024; K = 512; N = 1024; dst = (u16*)(p.ws + OFF_WBR + (l * 3 + (k - 4)) * SZ_WBR); break;
;       case 7: W = p.w_out + (size_t)l * 1024 * 1024; K = 1024; N = 1024; dst = (u16*)(p.ws + OFF_WOUT + l * SZ_WOUT); break;
;       case 8: W = p.w_ff1 + (size_t)l * 1024 * 4096; K = 1024; N = 4096; gain = p.ffn_norm + l * 1024; dst = (u16*)(p.ws + OFF_WFF1 + l * SZ_WFF1); break;
;       default: W = p.w_ff2 + (size_t)l * 4096 * 1024; K = 4096; N = 1024; dst = (u16*)(p.ws + OFF_WFF2 + l * SZ_WFF2); break;
;     }
.LBB1_122:
	s_mov_b32 s40, 0
	s_cmp_eq_u32 s73, 7
	s_cselect_b32 s40, 0x10000, s40
	s_cmp_eq_u32 s73, 8
	s_cselect_b32 s40, 0x40000, s40
	s_cmp_eq_u32 s73, 9
	s_cselect_b32 s40, 0x10000, s40
	s_cmp_eq_u32 s73, 17
	s_cselect_b32 s40, 0x10000, s40
	s_cmp_eq_u32 s73, 18
	s_cselect_b32 s40, 0x40000, s40
	s_cmp_eq_u32 s73, 19
	s_cselect_b32 s40, 0x10000, s40
	s_cmp_eq_u32 s73, 0
	s_cbranch_scc1 .Lprep_win1
	s_cmp_eq_u32 s73, 10
	s_cbranch_scc1 .Lprep_win1
	s_cmp_eq_u32 s40, 0
	s_cbranch_scc0 .Lprep_blk1
	v_ashrrev_i32_e32 v18, 31, v16
	v_mad_u64_u32 v[16:17], s[40:41], v16, s74, 0
	v_mov_b32_e32 v2, v17
	v_mad_u64_u32 v[18:19], s[40:41], v18, s74, v[2:3]
	v_mov_b32_e32 v17, v18
	v_lshl_add_u64 v[16:17], v[16:17], 1, v[4:5]
	s_branch .Lprep_st1

; DI int TID() { int t = (int)__builtin_amdgcn_workitem_id_x(); asm volatile("" : "+v"(t)); return t; }
; DI int BID() { int b = (int)__builtin_amdgcn_workgroup_id_x(); asm volatile("" : "+s"(b)); return b; }
; DI void tile_outproj(const Params& p, int l, const Chunk& ck, int tile, int next, PF& pf, char* smem) {
;   float* Cs = (float*)smem;
;   const int tid = TID(); const int mi = tile & (MTN - 1), ni = tile >> MTS; const int m0 = mi * 128, n0 = ni * 128;
;   f32x16 acc[2][2]; zero_acc(acc);
;   { const u16* Ap; const u16* Wt; outproj_ptrs(p, l, tile, Ap, Wt); gemm_run<16>(pf, Ap, 1024, Wt, acc, smem); }
;   if (next >= 0) { const u16* An; const u16* Wn; outproj_ptrs(p, l, next, An, Wn); gemm_issue(pf, An, 1024, Wn, 1024); }
;   acc_to_cs(acc, Cs);
; DI void run_phase(const Params& p, int ph, int l, int c, char* smem) {
;     ...
;     case PH_OUTPROJ: {
;       PF pf; int t = BID();
;       if (t < MTN * 8) { const u16* A0; const u16* W0; outproj_ptrs(p, l, t, A0, W0); gemm_issue(pf, A0, 1024, W0, 1024); }
;       for (; t < MTN * 8; t += gridDim.x) { const int tn = t + (int)gridDim.x; tile_outproj(p, l, ck, t, tn < MTN * 8 ? tn : -1, pf, smem); }
;     } break;
.LBB1_251:
	s_andn2_b64 vcc, exec, s[26:27]
	s_cbranch_vccnz .LBB1_257
	s_mov_b32 s35, s92
	s_bfe_u32 s0, s35, 0x10008
	s_bfe_u32 s20, s35, 0x20006
	s_andn2_b32 s35, s35, 0x1c0
	s_lshl_b32 s0, s0, 6
	s_lshl_b32 s20, s20, 7
	s_or_b32 s35, s35, s0
	s_or_b32 s35, s35, s20
	s_cmpk_gt_i32 s35, 0x3ff
	s_cbranch_scc1 .LBB1_257
	s_add_u32 s16, s18, 0x12080000
	s_addc_u32 s17, s19, 0
	s_lshl_b32 s0, s35, 18
	s_lshl_b32 s34, s35, 17
	s_and_b32 s0, s0, 0x1fc0000
	v_readlane_b32 s22, v255, 28
	s_add_u32 s20, s16, s0
	v_readlane_b32 s23, v255, 29
	s_addc_u32 s21, s17, 0
	s_ashr_i32 s23, s22, 31
	s_mov_b32 s0, s22
	v_writelane_b32 v255, s0, 28
	s_lshl_b64 s[22:23], s[22:23], 21
	v_writelane_b32 v255, s1, 29
	s_add_u32 s0, s18, s22
	s_addc_u32 s22, s19, s23
	s_add_u32 s36, s0, 0x2f80000
	s_addc_u32 s37, s22, 0
	s_and_b32 s22, s35, 0xffffff80
	s_ashr_i32 s23, s22, 31
	s_lshl_b64 s[22:23], s[22:23], 11
	s_add_u32 s22, s36, s22
	s_addc_u32 s23, s37, s23
	s_add_u32 s20, s18, 0x1c14c000
	s_addc_u32 s21, s19, 0
	s_add_u32 s22, s18, 0x1e24c000
	s_addc_u32 s23, s19, 0
	s_lshl_b32 s40, s35, 7
	s_branch .LBB1_255
.LBB1_254:
	s_add_i32 s40, s40, s95
	s_add_i32 s34, s34, s59
	s_and_b64 vcc, exec, s[24:25]
	s_mov_b32 s35, s41
	s_cbranch_vccnz .LBB1_257
.LBB1_255:
	s_add_i32 s41, s35, s78
	s_cmpk_gt_i32 s41, 0x1ff
	s_cselect_b64 s[24:25], -1, 0
	s_cmpk_lt_i32 s41, 0x200
	s_cselect_b32 s0, s41, -1
	s_and_b32 s27, s34, 0xfe0000
	s_and_b32 s26, s35, 0xffffff80
	s_lshl_b32 s26, s26, 1
	s_lshl_b32 s27, s27, 1
	s_add_u32 s28, s16, s27
	v_mov_b32_e32 v0, v172
	s_addc_u32 s29, s17, 0
	s_ashr_i32 s27, s26, 31
	s_lshl_b64 s[30:31], s[26:27], 6
	s_add_u32 s30, s36, s30
	s_addc_u32 s31, s37, s31
	s_setprio 0
	s_waitcnt lgkmcnt(0)
	v_and_b32_e32 v150, 63, v172
	v_lshrrev_b32_e32 v151, 6, v172
	v_bfe_u32 v152, v150, 4, 2
	v_lshrrev_b32_e32 v153, 1, v152
	v_xor_b32_e32 v152, v152, v153
	v_and_b32_e32 v152, 1, v152
	v_lshl_or_b32 v152, v152, 1, v153
	v_xor_b32_e32 v152, v152, v150
	v_and_b32_e32 v152, 3, v152
	v_lshlrev_b32_e32 v152, 4, v152
	v_lshrrev_b32_e32 v153, 2, v150
	v_lshl_add_u32 v143, v151, 5, v153
	v_lshl_add_u32 v143, v143, 11, v152
	v_add_u32_e32 v144, 0x7c00, v143
	v_lshl_add_u32 v145, v151, 6, v153
	v_lshl_add_u32 v145, v145, 6, v152
	v_mov_b32_e32 v146, v145
	v_mov_b32_e32 v147, v145
	v_mov_b32_e32 v148, v145
	v_readfirstlane_b32 s42, v151
	s_lshl_b32 s43, s42, 12
	s_lshl_b32 s42, s42, 11
	s_add_u32 s43, s43, 0x2000
	v_bfe_u32 v152, v150, 2, 2
	v_lshrrev_b32_e32 v153, 1, v152
	v_xor_b32_e32 v152, v152, v153
	v_and_b32_e32 v152, 1, v152
	v_lshl_or_b32 v152, v152, 1, v153
	v_lshrrev_b32_e32 v153, 4, v150
	v_xor_b32_e32 v152, v152, v153
	v_lshlrev_b32_e32 v152, 4, v152
	v_and_b32_e32 v150, 15, v150
	v_lshl_add_u32 v150, v150, 6, v152
	v_lshrrev_b32_e32 v152, 1, v151
	v_and_b32_e32 v153, 1, v151
	v_lshl_add_u32 v126, v152, 12, v150
	v_lshl_add_u32 v128, v153, 12, v150
	v_add_u32_e32 v128, 0x2000, v128
	s_barrier
	v_mov_b32_e32 v2, 0
	v_mov_b32_e32 v3, 0
	v_mov_b32_e32 v4, 0
	v_mov_b32_e32 v5, 0
	v_mov_b32_e32 v6, 0
	v_mov_b32_e32 v7, 0
	v_mov_b32_e32 v8, 0
	v_mov_b32_e32 v9, 0
	v_mov_b32_e32 v10, 0
	v_mov_b32_e32 v11, 0
	v_mov_b32_e32 v12, 0
	v_mov_b32_e32 v13, 0
	v_mov_b32_e32 v14, 0
	v_mov_b32_e32 v15, 0
	v_mov_b32_e32 v16, 0
	v_mov_b32_e32 v17, 0
	v_mov_b32_e32 v18, 0
	v_mov_b32_e32 v19, 0
	v_mov_b32_e32 v20, 0
	v_mov_b32_e32 v21, 0
	v_mov_b32_e32 v22, 0
	v_mov_b32_e32 v23, 0
	v_mov_b32_e32 v24, 0
	v_mov_b32_e32 v25, 0
	v_mov_b32_e32 v26, 0
	v_mov_b32_e32 v27, 0
	v_mov_b32_e32 v28, 0
	v_mov_b32_e32 v29, 0
	v_mov_b32_e32 v30, 0
	v_mov_b32_e32 v31, 0
	v_mov_b32_e32 v32, 0
	v_mov_b32_e32 v33, 0
	v_mov_b32_e32 v34, 0
	v_mov_b32_e32 v35, 0
	v_mov_b32_e32 v36, 0
	v_mov_b32_e32 v37, 0
	v_mov_b32_e32 v38, 0
	v_mov_b32_e32 v39, 0
	v_mov_b32_e32 v40, 0
	v_mov_b32_e32 v41, 0
	v_mov_b32_e32 v42, 0
	v_mov_b32_e32 v43, 0
	v_mov_b32_e32 v44, 0
	v_mov_b32_e32 v45, 0
	v_mov_b32_e32 v46, 0
	v_mov_b32_e32 v47, 0
	v_mov_b32_e32 v48, 0
	v_mov_b32_e32 v49, 0
	v_mov_b32_e32 v50, 0
	v_mov_b32_e32 v51, 0
	v_mov_b32_e32 v52, 0
	v_mov_b32_e32 v53, 0
	v_mov_b32_e32 v54, 0
	v_mov_b32_e32 v55, 0
	v_mov_b32_e32 v56, 0
	v_mov_b32_e32 v57, 0
	v_mov_b32_e32 v58, 0
	v_mov_b32_e32 v59, 0
	v_mov_b32_e32 v60, 0
	v_mov_b32_e32 v61, 0
	v_mov_b32_e32 v62, 0
	v_mov_b32_e32 v63, 0
	v_mov_b32_e32 v64, 0
	v_mov_b32_e32 v65, 0
	v_mov_b32_e32 v74, 0
	v_mov_b32_e32 v75, 0
	v_mov_b32_e32 v76, 0
	v_mov_b32_e32 v77, 0
	v_mov_b32_e32 v78, 0
	v_mov_b32_e32 v79, 0
	v_mov_b32_e32 v80, 0
	v_mov_b32_e32 v81, 0
	v_mov_b32_e32 v82, 0
	v_mov_b32_e32 v83, 0
	v_mov_b32_e32 v84, 0
	v_mov_b32_e32 v85, 0
	v_mov_b32_e32 v86, 0
	v_mov_b32_e32 v87, 0
	v_mov_b32_e32 v88, 0
	v_mov_b32_e32 v89, 0
	v_mov_b32_e32 v90, 0
	v_mov_b32_e32 v91, 0
	v_mov_b32_e32 v92, 0
	v_mov_b32_e32 v93, 0
	v_mov_b32_e32 v94, 0
	v_mov_b32_e32 v95, 0
	v_mov_b32_e32 v96, 0
	v_mov_b32_e32 v97, 0
	v_mov_b32_e32 v98, 0
	v_mov_b32_e32 v99, 0
	v_mov_b32_e32 v100, 0
	v_mov_b32_e32 v101, 0
	v_mov_b32_e32 v102, 0
	v_mov_b32_e32 v103, 0
	v_mov_b32_e32 v104, 0
	v_mov_b32_e32 v105, 0
	v_mov_b32_e32 v106, 0
	v_mov_b32_e32 v107, 0
	v_mov_b32_e32 v108, 0
	v_mov_b32_e32 v109, 0
	v_mov_b32_e32 v110, 0
	v_mov_b32_e32 v111, 0
	v_mov_b32_e32 v112, 0
	v_mov_b32_e32 v113, 0
	v_mov_b32_e32 v114, 0
	v_mov_b32_e32 v115, 0
	v_mov_b32_e32 v116, 0
	v_mov_b32_e32 v117, 0
	v_mov_b32_e32 v118, 0
	v_mov_b32_e32 v119, 0
	v_mov_b32_e32 v120, 0
	v_mov_b32_e32 v121, 0
	v_mov_b32_e32 v208, 0
	v_mov_b32_e32 v209, 0
	v_mov_b32_e32 v210, 0
	v_mov_b32_e32 v211, 0
	v_mov_b32_e32 v212, 0
	v_mov_b32_e32 v213, 0
	v_mov_b32_e32 v214, 0
	v_mov_b32_e32 v215, 0
	v_mov_b32_e32 v216, 0
	v_mov_b32_e32 v217, 0
	v_mov_b32_e32 v218, 0
	v_mov_b32_e32 v219, 0
	v_mov_b32_e32 v220, 0
	v_mov_b32_e32 v221, 0
	v_mov_b32_e32 v222, 0
	v_mov_b32_e32 v223, 0
	s_add_u32 m0, s42, 0x0
	s_nop 0
	global_load_lds_dwordx4 v143, s[28:29]
	global_load_lds_dwordx4 v144, s[28:29] offset:1024
	s_add_u32 m0, s43, 0x0
	s_nop 0
	global_load_lds_dwordx4 v145, s[30:31]
	global_load_lds_dwordx4 v146, s[30:31] offset:1024
	global_load_lds_dwordx4 v147, s[30:31] offset:2048
	global_load_lds_dwordx4 v148, s[30:31] offset:3072
	s_add_u32 m0, s42, 0x6000
	s_add_u32 s28, s28, 0x40
	s_addc_u32 s29, s29, 0
	global_load_lds_dwordx4 v143, s[28:29]
	global_load_lds_dwordx4 v144, s[28:29] offset:1024
	s_add_u32 m0, s43, 0x6000
	s_add_u32 s30, s30, 0x10000
	s_addc_u32 s31, s31, 0
	global_load_lds_dwordx4 v145, s[30:31]
	global_load_lds_dwordx4 v146, s[30:31] offset:1024
	global_load_lds_dwordx4 v147, s[30:31] offset:2048
	global_load_lds_dwordx4 v148, s[30:31] offset:3072
	s_mov_b32 s46, 10
; #define BLOAD(A_, B_, kt) do { _Pragma("unroll") for (int i = 0; i < 4; ++i) { \
;     A_[i] = *(const u32x4*)((const char*)Ap + (aoff + (unsigned)(32 * i * lda + (kt) * 64) * 2u)); B_[i] = *(const u32x4*)((const char*)Wt + (woff + (unsigned)(32 * i * K + (kt) * 64) * 2u)); } } while (0)
; #define BLOAD(A_, B_, kt) do { _Pragma("unroll") for (int i = 0; i < 4; ++i) { \
;     A_[i] = *(const u32x4*)((const char*)Ap + (aoff + (unsigned)(32 * i * lda + (kt) * 64) * 2u)); B_[i] = *(const u32x4*)((const char*)Wt + (woff + (unsigned)(32 * i * K + (kt) * 64) * 2u)); } } while (0)
; #define BSTORE(A_, B_, buf) do { _Pragma("unroll") for (int i = 0; i < 4; ++i) { \
;     *(u32x4*)&As[(buf) * GBUF + (srow + 32 * i) * LDT + sc8] = A_[i]; \
;     *(u32x4*)&Bs[(buf) * GBUF + (srow + 32 * i) * LDT + sc8] = B_[i]; } } while (0)
; template <int NK>
; DI void gemm_run(PF& pf, const u16* __restrict__ Ap, int lda, const u16* __restrict__ Wt, f32x16 (&acc)[2][2], char* smem) {
;     ...
;   __builtin_amdgcn_s_setprio(0);
;   __syncthreads();
;   BSTORE(pf.a0, pf.b0, 0);
;   BLOAD(pf.a0, pf.b0, 2);
;   __syncthreads();
; #pragma unroll
;   for (int kt = 0; kt < nk; kt += 2) {
;     BCOMP(0);
;     BSTORE(pf.a1, pf.b1, 1);
;     if (kt + 3 < nk) BLOAD(pf.a1, pf.b1, kt + 3);
;     __syncthreads();
;     BCOMP(1);
;     if (kt + 2 < nk) { BSTORE(pf.a0, pf.b0, 0); if (kt + 4 < nk) BLOAD(pf.a0, pf.b0, kt + 4); }
;     __syncthreads();
;   }
.Lout_kloop:
	s_waitcnt vmcnt(6)
	s_barrier
	ds_read_b128 v[224:227], v126 offset:0
	ds_read_b128 v[240:243], v128 offset:0
	ds_read_b128 v[244:247], v128 offset:1024
	ds_read_b128 v[248:251], v128 offset:2048
	ds_read_b128 v[156:159], v128 offset:3072
	s_add_u32 m0, s42, 0xc000
	s_add_u32 s28, s28, 0x40
	s_addc_u32 s29, s29, 0
	global_load_lds_dwordx4 v143, s[28:29]
	global_load_lds_dwordx4 v144, s[28:29] offset:1024
	s_add_u32 m0, s43, 0xc000
	s_add_u32 s30, s30, 0x10000
	s_addc_u32 s31, s31, 0
	global_load_lds_dwordx4 v145, s[30:31]
	global_load_lds_dwordx4 v146, s[30:31] offset:1024
	global_load_lds_dwordx4 v147, s[30:31] offset:2048
	global_load_lds_dwordx4 v148, s[30:31] offset:3072
	ds_read_b128 v[228:231], v126 offset:1024
	ds_read_b128 v[232:235], v126 offset:2048
	ds_read_b128 v[236:239], v126 offset:3072
	ds_read_b128 v[160:163], v128 offset:8192
	ds_read_b128 v[164:167], v128 offset:9216
	ds_read_b128 v[168:171], v128 offset:10240
	ds_read_b128 v[122:125], v128 offset:11264
	s_waitcnt lgkmcnt(10)
	v_mfma_f32_16x16x32_bf16 v[2:5], v[240:243], v[224:227], v[2:5]
	s_waitcnt lgkmcnt(9)
	v_mfma_f32_16x16x32_bf16 v[6:9], v[244:247], v[224:227], v[6:9]
	s_waitcnt lgkmcnt(8)
	v_mfma_f32_16x16x32_bf16 v[10:13], v[248:251], v[224:227], v[10:13]
	s_waitcnt lgkmcnt(7)
	v_mfma_f32_16x16x32_bf16 v[14:17], v[156:159], v[224:227], v[14:17]
	s_waitcnt lgkmcnt(6)
	v_mfma_f32_16x16x32_bf16 v[18:21], v[240:243], v[228:231], v[18:21]
	v_mfma_f32_16x16x32_bf16 v[22:25], v[244:247], v[228:231], v[22:25]
	v_mfma_f32_16x16x32_bf16 v[26:29], v[248:251], v[228:231], v[26:29]
	v_mfma_f32_16x16x32_bf16 v[30:33], v[156:159], v[228:231], v[30:33]
	s_waitcnt lgkmcnt(5)
	v_mfma_f32_16x16x32_bf16 v[34:37], v[240:243], v[232:235], v[34:37]
	v_mfma_f32_16x16x32_bf16 v[38:41], v[244:247], v[232:235], v[38:41]
	v_mfma_f32_16x16x32_bf16 v[42:45], v[248:251], v[232:235], v[42:45]
	v_mfma_f32_16x16x32_bf16 v[46:49], v[156:159], v[232:235], v[46:49]
	s_waitcnt lgkmcnt(4)
	v_mfma_f32_16x16x32_bf16 v[50:53], v[240:243], v[236:239], v[50:53]
	v_mfma_f32_16x16x32_bf16 v[54:57], v[244:247], v[236:239], v[54:57]
	v_mfma_f32_16x16x32_bf16 v[58:61], v[248:251], v[236:239], v[58:61]
	v_mfma_f32_16x16x32_bf16 v[62:65], v[156:159], v[236:239], v[62:65]
	s_waitcnt lgkmcnt(3)
	v_mfma_f32_16x16x32_bf16 v[74:77], v[160:163], v[224:227], v[74:77]
	s_waitcnt lgkmcnt(2)
	v_mfma_f32_16x16x32_bf16 v[78:81], v[164:167], v[224:227], v[78:81]
	s_waitcnt lgkmcnt(1)
	v_mfma_f32_16x16x32_bf16 v[82:85], v[168:171], v[224:227], v[82:85]
	s_waitcnt lgkmcnt(0)
	v_mfma_f32_16x16x32_bf16 v[86:89], v[122:125], v[224:227], v[86:89]
	v_mfma_f32_16x16x32_bf16 v[90:93], v[160:163], v[228:231], v[90:93]
	v_mfma_f32_16x16x32_bf16 v[94:97], v[164:167], v[228:231], v[94:97]
	v_mfma_f32_16x16x32_bf16 v[98:101], v[168:171], v[228:231], v[98:101]
	v_mfma_f32_16x16x32_bf16 v[102:105], v[122:125], v[228:231], v[102:105]
	v_mfma_f32_16x16x32_bf16 v[106:109], v[160:163], v[232:235], v[106:109]
	v_mfma_f32_16x16x32_bf16 v[110:113], v[164:167], v[232:235], v[110:113]
	v_mfma_f32_16x16x32_bf16 v[114:117], v[168:171], v[232:235], v[114:117]
	v_mfma_f32_16x16x32_bf16 v[118:121], v[122:125], v[232:235], v[118:121]
	v_mfma_f32_16x16x32_bf16 v[208:211], v[160:163], v[236:239], v[208:211]
	v_mfma_f32_16x16x32_bf16 v[212:215], v[164:167], v[236:239], v[212:215]
	v_mfma_f32_16x16x32_bf16 v[216:219], v[168:171], v[236:239], v[216:219]
	v_mfma_f32_16x16x32_bf16 v[220:223], v[122:125], v[236:239], v[220:223]
	s_waitcnt vmcnt(6)
	s_barrier
	ds_read_b128 v[224:227], v126 offset:24576
	ds_read_b128 v[240:243], v128 offset:24576
	ds_read_b128 v[244:247], v128 offset:25600
	ds_read_b128 v[248:251], v128 offset:26624
	ds_read_b128 v[156:159], v128 offset:27648
	s_add_u32 m0, s42, 0x0
	s_add_u32 s28, s28, 0x40
	s_addc_u32 s29, s29, 0
	global_load_lds_dwordx4 v143, s[28:29]
	global_load_lds_dwordx4 v144, s[28:29] offset:1024
	s_add_u32 m0, s43, 0x0
	s_add_u32 s30, s30, 0x10000
	s_addc_u32 s31, s31, 0
	global_load_lds_dwordx4 v145, s[30:31]
	global_load_lds_dwordx4 v146, s[30:31] offset:1024
	global_load_lds_dwordx4 v147, s[30:31] offset:2048
	global_load_lds_dwordx4 v148, s[30:31] offset:3072
	ds_read_b128 v[228:231], v126 offset:25600
	ds_read_b128 v[232:235], v126 offset:26624
	ds_read_b128 v[236:239], v126 offset:27648
	ds_read_b128 v[160:163], v128 offset:32768
	ds_read_b128 v[164:167], v128 offset:33792
	ds_read_b128 v[168:171], v128 offset:34816
	ds_read_b128 v[122:125], v128 offset:35840
	s_waitcnt lgkmcnt(10)
	v_mfma_f32_16x16x32_bf16 v[2:5], v[240:243], v[224:227], v[2:5]
	s_waitcnt lgkmcnt(9)
	v_mfma_f32_16x16x32_bf16 v[6:9], v[244:247], v[224:227], v[6:9]
	s_waitcnt lgkmcnt(8)
	v_mfma_f32_16x16x32_bf16 v[10:13], v[248:251], v[224:227], v[10:13]
	s_waitcnt lgkmcnt(7)
	v_mfma_f32_16x16x32_bf16 v[14:17], v[156:159], v[224:227], v[14:17]
	s_waitcnt lgkmcnt(6)
	v_mfma_f32_16x16x32_bf16 v[18:21], v[240:243], v[228:231], v[18:21]
	v_mfma_f32_16x16x32_bf16 v[22:25], v[244:247], v[228:231], v[22:25]
	v_mfma_f32_16x16x32_bf16 v[26:29], v[248:251], v[228:231], v[26:29]
	v_mfma_f32_16x16x32_bf16 v[30:33], v[156:159], v[228:231], v[30:33]
	s_waitcnt lgkmcnt(5)
	v_mfma_f32_16x16x32_bf16 v[34:37], v[240:243], v[232:235], v[34:37]
	v_mfma_f32_16x16x32_bf16 v[38:41], v[244:247], v[232:235], v[38:41]
	v_mfma_f32_16x16x32_bf16 v[42:45], v[248:251], v[232:235], v[42:45]
	v_mfma_f32_16x16x32_bf16 v[46:49], v[156:159], v[232:235], v[46:49]
	s_waitcnt lgkmcnt(4)
	v_mfma_f32_16x16x32_bf16 v[50:53], v[240:243], v[236:239], v[50:53]
	v_mfma_f32_16x16x32_bf16 v[54:57], v[244:247], v[236:239], v[54:57]
	v_mfma_f32_16x16x32_bf16 v[58:61], v[248:251], v[236:239], v[58:61]
	v_mfma_f32_16x16x32_bf16 v[62:65], v[156:159], v[236:239], v[62:65]
	s_waitcnt lgkmcnt(3)
	v_mfma_f32_16x16x32_bf16 v[74:77], v[160:163], v[224:227], v[74:77]
	s_waitcnt lgkmcnt(2)
	v_mfma_f32_16x16x32_bf16 v[78:81], v[164:167], v[224:227], v[78:81]
	s_waitcnt lgkmcnt(1)
	v_mfma_f32_16x16x32_bf16 v[82:85], v[168:171], v[224:227], v[82:85]
	s_waitcnt lgkmcnt(0)
	v_mfma_f32_16x16x32_bf16 v[86:89], v[122:125], v[224:227], v[86:89]
	v_mfma_f32_16x16x32_bf16 v[90:93], v[160:163], v[228:231], v[90:93]
	v_mfma_f32_16x16x32_bf16 v[94:97], v[164:167], v[228:231], v[94:97]
	v_mfma_f32_16x16x32_bf16 v[98:101], v[168:171], v[228:231], v[98:101]
	v_mfma_f32_16x16x32_bf16 v[102:105], v[122:125], v[228:231], v[102:105]
	v_mfma_f32_16x16x32_bf16 v[106:109], v[160:163], v[232:235], v[106:109]
	v_mfma_f32_16x16x32_bf16 v[110:113], v[164:167], v[232:235], v[110:113]
	v_mfma_f32_16x16x32_bf16 v[114:117], v[168:171], v[232:235], v[114:117]
	v_mfma_f32_16x16x32_bf16 v[118:121], v[122:125], v[232:235], v[118:121]
	v_mfma_f32_16x16x32_bf16 v[208:211], v[160:163], v[236:239], v[208:211]
	v_mfma_f32_16x16x32_bf16 v[212:215], v[164:167], v[236:239], v[212:215]
	v_mfma_f32_16x16x32_bf16 v[216:219], v[168:171], v[236:239], v[216:219]
	v_mfma_f32_16x16x32_bf16 v[220:223], v[122:125], v[236:239], v[220:223]
	s_waitcnt vmcnt(6)
	s_barrier
; #define BLOAD(A_, B_, kt) do { _Pragma("unroll") for (int i = 0; i < 4; ++i) { \
;     A_[i] = *(const u32x4*)((const char*)Ap + (aoff + (unsigned)(32 * i * lda + (kt) * 64) * 2u)); B_[i] = *(const u32x4*)((const char*)Wt + (woff + (unsigned)(32 * i * K + (kt) * 64) * 2u)); } } while (0)
; #define BLOAD(A_, B_, kt) do { _Pragma("unroll") for (int i = 0; i < 4; ++i) { \
;     A_[i] = *(const u32x4*)((const char*)Ap + (aoff + (unsigned)(32 * i * lda + (kt) * 64) * 2u)); B_[i] = *(const u32x4*)((const char*)Wt + (woff + (unsigned)(32 * i * K + (kt) * 64) * 2u)); } } while (0)
; #define BSTORE(A_, B_, buf) do { _Pragma("unroll") for (int i = 0; i < 4; ++i) { \
;     *(u32x4*)&As[(buf) * GBUF + (srow + 32 * i) * LDT + sc8] = A_[i]; \
;     *(u32x4*)&Bs[(buf) * GBUF + (srow + 32 * i) * LDT + sc8] = B_[i]; } } while (0)
; template <int NK>
; DI void gemm_run(PF& pf, const u16* __restrict__ Ap, int lda, const u16* __restrict__ Wt, f32x16 (&acc)[2][2], char* smem) {
;     ...
;   __builtin_amdgcn_s_setprio(0);
;   __syncthreads();
;   BSTORE(pf.a0, pf.b0, 0);
;   BLOAD(pf.a0, pf.b0, 2);
;   __syncthreads();
; #pragma unroll
;   for (int kt = 0; kt < nk; kt += 2) {
;     BCOMP(0);
;     BSTORE(pf.a1, pf.b1, 1);
;     if (kt + 3 < nk) BLOAD(pf.a1, pf.b1, kt + 3);
;     __syncthreads();
;     BCOMP(1);
;     if (kt + 2 < nk) { BSTORE(pf.a0, pf.b0, 0); if (kt + 4 < nk) BLOAD(pf.a0, pf.b0, kt + 4); }
;     __syncthreads();
;   }
	ds_read_b128 v[224:227], v126 offset:49152
	ds_read_b128 v[240:243], v128 offset:49152
	ds_read_b128 v[244:247], v128 offset:50176
	ds_read_b128 v[248:251], v128 offset:51200
	ds_read_b128 v[156:159], v128 offset:52224
	s_add_u32 m0, s42, 0x6000
	s_add_u32 s28, s28, 0x40
	s_addc_u32 s29, s29, 0
	global_load_lds_dwordx4 v143, s[28:29]
	global_load_lds_dwordx4 v144, s[28:29] offset:1024
	s_add_u32 m0, s43, 0x6000
	s_add_u32 s30, s30, 0x10000
	s_addc_u32 s31, s31, 0
	global_load_lds_dwordx4 v145, s[30:31]
	global_load_lds_dwordx4 v146, s[30:31] offset:1024
	global_load_lds_dwordx4 v147, s[30:31] offset:2048
	global_load_lds_dwordx4 v148, s[30:31] offset:3072
	ds_read_b128 v[228:231], v126 offset:50176
	ds_read_b128 v[232:235], v126 offset:51200
	ds_read_b128 v[236:239], v126 offset:52224
	ds_read_b128 v[160:163], v128 offset:57344
	ds_read_b128 v[164:167], v128 offset:58368
	ds_read_b128 v[168:171], v128 offset:59392
	ds_read_b128 v[122:125], v128 offset:60416
	s_waitcnt lgkmcnt(10)
	v_mfma_f32_16x16x32_bf16 v[2:5], v[240:243], v[224:227], v[2:5]
	s_waitcnt lgkmcnt(9)
	v_mfma_f32_16x16x32_bf16 v[6:9], v[244:247], v[224:227], v[6:9]
	s_waitcnt lgkmcnt(8)
	v_mfma_f32_16x16x32_bf16 v[10:13], v[248:251], v[224:227], v[10:13]
	s_waitcnt lgkmcnt(7)
	v_mfma_f32_16x16x32_bf16 v[14:17], v[156:159], v[224:227], v[14:17]
	s_waitcnt lgkmcnt(6)
	v_mfma_f32_16x16x32_bf16 v[18:21], v[240:243], v[228:231], v[18:21]
	v_mfma_f32_16x16x32_bf16 v[22:25], v[244:247], v[228:231], v[22:25]
	v_mfma_f32_16x16x32_bf16 v[26:29], v[248:251], v[228:231], v[26:29]
	v_mfma_f32_16x16x32_bf16 v[30:33], v[156:159], v[228:231], v[30:33]
	s_waitcnt lgkmcnt(5)
	v_mfma_f32_16x16x32_bf16 v[34:37], v[240:243], v[232:235], v[34:37]
	v_mfma_f32_16x16x32_bf16 v[38:41], v[244:247], v[232:235], v[38:41]
	v_mfma_f32_16x16x32_bf16 v[42:45], v[248:251], v[232:235], v[42:45]
	v_mfma_f32_16x16x32_bf16 v[46:49], v[156:159], v[232:235], v[46:49]
	s_waitcnt lgkmcnt(4)
	v_mfma_f32_16x16x32_bf16 v[50:53], v[240:243], v[236:239], v[50:53]
	v_mfma_f32_16x16x32_bf16 v[54:57], v[244:247], v[236:239], v[54:57]
	v_mfma_f32_16x16x32_bf16 v[58:61], v[248:251], v[236:239], v[58:61]
	v_mfma_f32_16x16x32_bf16 v[62:65], v[156:159], v[236:239], v[62:65]
	s_waitcnt lgkmcnt(3)
	v_mfma_f32_16x16x32_bf16 v[74:77], v[160:163], v[224:227], v[74:77]
	s_waitcnt lgkmcnt(2)
	v_mfma_f32_16x16x32_bf16 v[78:81], v[164:167], v[224:227], v[78:81]
	s_waitcnt lgkmcnt(1)
	v_mfma_f32_16x16x32_bf16 v[82:85], v[168:171], v[224:227], v[82:85]
	s_waitcnt lgkmcnt(0)
	v_mfma_f32_16x16x32_bf16 v[86:89], v[122:125], v[224:227], v[86:89]
	v_mfma_f32_16x16x32_bf16 v[90:93], v[160:163], v[228:231], v[90:93]
	v_mfma_f32_16x16x32_bf16 v[94:97], v[164:167], v[228:231], v[94:97]
	v_mfma_f32_16x16x32_bf16 v[98:101], v[168:171], v[228:231], v[98:101]
	v_mfma_f32_16x16x32_bf16 v[102:105], v[122:125], v[228:231], v[102:105]
	v_mfma_f32_16x16x32_bf16 v[106:109], v[160:163], v[232:235], v[106:109]
	v_mfma_f32_16x16x32_bf16 v[110:113], v[164:167], v[232:235], v[110:113]
	v_mfma_f32_16x16x32_bf16 v[114:117], v[168:171], v[232:235], v[114:117]
	v_mfma_f32_16x16x32_bf16 v[118:121], v[122:125], v[232:235], v[118:121]
	v_mfma_f32_16x16x32_bf16 v[208:211], v[160:163], v[236:239], v[208:211]
	v_mfma_f32_16x16x32_bf16 v[212:215], v[164:167], v[236:239], v[212:215]
	v_mfma_f32_16x16x32_bf16 v[216:219], v[168:171], v[236:239], v[216:219]
	v_mfma_f32_16x16x32_bf16 v[220:223], v[122:125], v[236:239], v[220:223]
	s_sub_u32 s46, s46, 1
	s_cmp_lg_u32 s46, 0
	s_cbranch_scc1 .Lout_kloop
	s_waitcnt vmcnt(6)
	s_barrier
	ds_read_b128 v[224:227], v126 offset:0
	ds_read_b128 v[240:243], v128 offset:0
	ds_read_b128 v[244:247], v128 offset:1024
	ds_read_b128 v[248:251], v128 offset:2048
	ds_read_b128 v[156:159], v128 offset:3072
	ds_read_b128 v[228:231], v126 offset:1024
	ds_read_b128 v[232:235], v126 offset:2048
	ds_read_b128 v[236:239], v126 offset:3072
	ds_read_b128 v[160:163], v128 offset:8192
	ds_read_b128 v[164:167], v128 offset:9216
	ds_read_b128 v[168:171], v128 offset:10240
	ds_read_b128 v[122:125], v128 offset:11264
	s_waitcnt lgkmcnt(10)
	v_mfma_f32_16x16x32_bf16 v[2:5], v[240:243], v[224:227], v[2:5]
	s_waitcnt lgkmcnt(9)
	v_mfma_f32_16x16x32_bf16 v[6:9], v[244:247], v[224:227], v[6:9]
	s_waitcnt lgkmcnt(8)
	v_mfma_f32_16x16x32_bf16 v[10:13], v[248:251], v[224:227], v[10:13]
	s_waitcnt lgkmcnt(7)
	v_mfma_f32_16x16x32_bf16 v[14:17], v[156:159], v[224:227], v[14:17]
	s_waitcnt lgkmcnt(6)
	v_mfma_f32_16x16x32_bf16 v[18:21], v[240:243], v[228:231], v[18:21]
	v_mfma_f32_16x16x32_bf16 v[22:25], v[244:247], v[228:231], v[22:25]
	v_mfma_f32_16x16x32_bf16 v[26:29], v[248:251], v[228:231], v[26:29]
	v_mfma_f32_16x16x32_bf16 v[30:33], v[156:159], v[228:231], v[30:33]
	s_waitcnt lgkmcnt(5)
	v_mfma_f32_16x16x32_bf16 v[34:37], v[240:243], v[232:235], v[34:37]
	v_mfma_f32_16x16x32_bf16 v[38:41], v[244:247], v[232:235], v[38:41]
	v_mfma_f32_16x16x32_bf16 v[42:45], v[248:251], v[232:235], v[42:45]
	v_mfma_f32_16x16x32_bf16 v[46:49], v[156:159], v[232:235], v[46:49]
	s_waitcnt lgkmcnt(4)
	v_mfma_f32_16x16x32_bf16 v[50:53], v[240:243], v[236:239], v[50:53]
	v_mfma_f32_16x16x32_bf16 v[54:57], v[244:247], v[236:239], v[54:57]
	v_mfma_f32_16x16x32_bf16 v[58:61], v[248:251], v[236:239], v[58:61]
	v_mfma_f32_16x16x32_bf16 v[62:65], v[156:159], v[236:239], v[62:65]
	s_waitcnt lgkmcnt(3)
	v_mfma_f32_16x16x32_bf16 v[74:77], v[160:163], v[224:227], v[74:77]
	s_waitcnt lgkmcnt(2)
	v_mfma_f32_16x16x32_bf16 v[78:81], v[164:167], v[224:227], v[78:81]
	s_waitcnt lgkmcnt(1)
	v_mfma_f32_16x16x32_bf16 v[82:85], v[168:171], v[224:227], v[82:85]
	s_waitcnt lgkmcnt(0)
	v_mfma_f32_16x16x32_bf16 v[86:89], v[122:125], v[224:227], v[86:89]
	v_mfma_f32_16x16x32_bf16 v[90:93], v[160:163], v[228:231], v[90:93]
	v_mfma_f32_16x16x32_bf16 v[94:97], v[164:167], v[228:231], v[94:97]
	v_mfma_f32_16x16x32_bf16 v[98:101], v[168:171], v[228:231], v[98:101]
	v_mfma_f32_16x16x32_bf16 v[102:105], v[122:125], v[228:231], v[102:105]
	v_mfma_f32_16x16x32_bf16 v[106:109], v[160:163], v[232:235], v[106:109]
	v_mfma_f32_16x16x32_bf16 v[110:113], v[164:167], v[232:235], v[110:113]
	v_mfma_f32_16x16x32_bf16 v[114:117], v[168:171], v[232:235], v[114:117]
	v_mfma_f32_16x16x32_bf16 v[118:121], v[122:125], v[232:235], v[118:121]
	v_mfma_f32_16x16x32_bf16 v[208:211], v[160:163], v[236:239], v[208:211]
	v_mfma_f32_16x16x32_bf16 v[212:215], v[164:167], v[236:239], v[212:215]
	v_mfma_f32_16x16x32_bf16 v[216:219], v[168:171], v[236:239], v[216:219]
	v_mfma_f32_16x16x32_bf16 v[220:223], v[122:125], v[236:239], v[220:223]
	s_waitcnt vmcnt(0)
	s_barrier
; #define BLOAD(A_, B_, kt) do { _Pragma("unroll") for (int i = 0; i < 4; ++i) { \
;     A_[i] = *(const u32x4*)((const char*)Ap + (aoff + (unsigned)(32 * i * lda + (kt) * 64) * 2u)); B_[i] = *(const u32x4*)((const char*)Wt + (woff + (unsigned)(32 * i * K + (kt) * 64) * 2u)); } } while (0)
; #define BLOAD(A_, B_, kt) do { _Pragma("unroll") for (int i = 0; i < 4; ++i) { \
;     A_[i] = *(const u32x4*)((const char*)Ap + (aoff + (unsigned)(32 * i * lda + (kt) * 64) * 2u)); B_[i] = *(const u32x4*)((const char*)Wt + (woff + (unsigned)(32 * i * K + (kt) * 64) * 2u)); } } while (0)
; #define BSTORE(A_, B_, buf) do { _Pragma("unroll") for (int i = 0; i < 4; ++i) { \
;     *(u32x4*)&As[(buf) * GBUF + (srow + 32 * i) * LDT + sc8] = A_[i]; \
;     *(u32x4*)&Bs[(buf) * GBUF + (srow + 32 * i) * LDT + sc8] = B_[i]; } } while (0)
; template <int NK>
; DI void gemm_run(PF& pf, const u16* __restrict__ Ap, int lda, const u16* __restrict__ Wt, f32x16 (&acc)[2][2], char* smem) {
;     ...
; #pragma unroll
;   for (int kt = 0; kt < nk; kt += 2) {
;     BCOMP(0);
;     BSTORE(pf.a1, pf.b1, 1);
;     if (kt + 3 < nk) BLOAD(pf.a1, pf.b1, kt + 3);
;     __syncthreads();
;     BCOMP(1);
;     if (kt + 2 < nk) { BSTORE(pf.a0, pf.b0, 0); if (kt + 4 < nk) BLOAD(pf.a0, pf.b0, kt + 4); }
;     __syncthreads();
;   }
; DI void tile_outproj(const Params& p, int l, const Chunk& ck, int tile, int next, PF& pf, char* smem) {
;     ...
;   const int row = tid >> 1, half = tid & 1; float ssq = 0.f;
;   u16* xb = (u16*)(p.ws + OFF_XB) + (size_t)(m0 + row) * 1024 + n0 + half * 64;
; #pragma unroll
;   for (int c8 = 0; c8 < 8; ++c8) {
;     float v[8], x[8]; cs_ld8(Cs, row, half * 64 + c8 * 8, v); unpack8(*(const u32x4*)(xb + c8 * 8), x);
	ds_read_b128 v[224:227], v126 offset:24576
	ds_read_b128 v[240:243], v128 offset:24576
	ds_read_b128 v[244:247], v128 offset:25600
	ds_read_b128 v[248:251], v128 offset:26624
	ds_read_b128 v[156:159], v128 offset:27648
	ds_read_b128 v[228:231], v126 offset:25600
	ds_read_b128 v[232:235], v126 offset:26624
	ds_read_b128 v[236:239], v126 offset:27648
	ds_read_b128 v[160:163], v128 offset:32768
	ds_read_b128 v[164:167], v128 offset:33792
	ds_read_b128 v[168:171], v128 offset:34816
	ds_read_b128 v[122:125], v128 offset:35840
	s_waitcnt lgkmcnt(10)
	v_mfma_f32_16x16x32_bf16 v[2:5], v[240:243], v[224:227], v[2:5]
	s_waitcnt lgkmcnt(9)
	v_mfma_f32_16x16x32_bf16 v[6:9], v[244:247], v[224:227], v[6:9]
	s_waitcnt lgkmcnt(8)
	v_mfma_f32_16x16x32_bf16 v[10:13], v[248:251], v[224:227], v[10:13]
	s_waitcnt lgkmcnt(7)
	v_mfma_f32_16x16x32_bf16 v[14:17], v[156:159], v[224:227], v[14:17]
	s_waitcnt lgkmcnt(6)
	v_mfma_f32_16x16x32_bf16 v[18:21], v[240:243], v[228:231], v[18:21]
	v_mfma_f32_16x16x32_bf16 v[22:25], v[244:247], v[228:231], v[22:25]
	v_mfma_f32_16x16x32_bf16 v[26:29], v[248:251], v[228:231], v[26:29]
	v_mfma_f32_16x16x32_bf16 v[30:33], v[156:159], v[228:231], v[30:33]
	s_waitcnt lgkmcnt(5)
	v_mfma_f32_16x16x32_bf16 v[34:37], v[240:243], v[232:235], v[34:37]
	v_mfma_f32_16x16x32_bf16 v[38:41], v[244:247], v[232:235], v[38:41]
	v_mfma_f32_16x16x32_bf16 v[42:45], v[248:251], v[232:235], v[42:45]
	v_mfma_f32_16x16x32_bf16 v[46:49], v[156:159], v[232:235], v[46:49]
	s_waitcnt lgkmcnt(4)
	v_mfma_f32_16x16x32_bf16 v[50:53], v[240:243], v[236:239], v[50:53]
	v_mfma_f32_16x16x32_bf16 v[54:57], v[244:247], v[236:239], v[54:57]
	v_mfma_f32_16x16x32_bf16 v[58:61], v[248:251], v[236:239], v[58:61]
	v_mfma_f32_16x16x32_bf16 v[62:65], v[156:159], v[236:239], v[62:65]
	s_waitcnt lgkmcnt(3)
	v_mfma_f32_16x16x32_bf16 v[74:77], v[160:163], v[224:227], v[74:77]
	s_waitcnt lgkmcnt(2)
	v_mfma_f32_16x16x32_bf16 v[78:81], v[164:167], v[224:227], v[78:81]
	s_waitcnt lgkmcnt(1)
	v_mfma_f32_16x16x32_bf16 v[82:85], v[168:171], v[224:227], v[82:85]
	s_waitcnt lgkmcnt(0)
	v_mfma_f32_16x16x32_bf16 v[86:89], v[122:125], v[224:227], v[86:89]
	v_mfma_f32_16x16x32_bf16 v[90:93], v[160:163], v[228:231], v[90:93]
	v_mfma_f32_16x16x32_bf16 v[94:97], v[164:167], v[228:231], v[94:97]
	v_mfma_f32_16x16x32_bf16 v[98:101], v[168:171], v[228:231], v[98:101]
	v_mfma_f32_16x16x32_bf16 v[102:105], v[122:125], v[228:231], v[102:105]
	v_mfma_f32_16x16x32_bf16 v[106:109], v[160:163], v[232:235], v[106:109]
	v_mfma_f32_16x16x32_bf16 v[110:113], v[164:167], v[232:235], v[110:113]
	v_mfma_f32_16x16x32_bf16 v[114:117], v[168:171], v[232:235], v[114:117]
	v_mfma_f32_16x16x32_bf16 v[118:121], v[122:125], v[232:235], v[118:121]
	v_mfma_f32_16x16x32_bf16 v[208:211], v[160:163], v[236:239], v[208:211]
	v_mfma_f32_16x16x32_bf16 v[212:215], v[164:167], v[236:239], v[212:215]
	v_mfma_f32_16x16x32_bf16 v[216:219], v[168:171], v[236:239], v[216:219]
	v_mfma_f32_16x16x32_bf16 v[220:223], v[122:125], v[236:239], v[220:223]
	s_barrier
	s_and_b32 s0, s40, 0x3f80
	v_and_b32_e32 v160, 63, v172
	v_lshrrev_b32_e32 v161, 6, v172
	v_and_b32_e32 v162, 15, v160
	v_lshrrev_b32_e32 v163, 4, v160
	v_lshrrev_b32_e32 v167, 1, v161
	v_lshl_add_u32 v167, v167, 6, v162
	v_and_b32_e32 v168, 1, v161
	v_lshlrev_b32_e32 v169, 6, v168
	v_lshl_add_u32 v169, v163, 2, v169
	v_add_u32_e32 v169, s26, v169
	v_add_u32_e32 v170, s0, v167
	v_lshlrev_b32_e32 v164, 11, v170
	v_lshl_add_u32 v164, v169, 1, v164
	v_lshlrev_b32_e32 v165, 12, v167
	v_lshl_add_u32 v165, v169, 2, v165
	v_lshlrev_b32_e32 v166, 6, v170
	v_lshl_add_u32 v166, v168, 2, v166
	s_lshr_b32 s0, s26, 4
	s_add_u32 s14, s22, s0
	s_addc_u32 s15, s23, 0
	global_load_dwordx2 v[224:225], v164, s[20:21] offset:0
	global_load_dwordx2 v[226:227], v164, s[20:21] offset:32
	global_load_dwordx2 v[228:229], v164, s[20:21] offset:64
	global_load_dwordx2 v[230:231], v164, s[20:21] offset:96
	v_add_u32_e32 v164, 0x8000, v164
	global_load_dwordx2 v[232:233], v164, s[20:21] offset:0
	global_load_dwordx2 v[234:235], v164, s[20:21] offset:32
	global_load_dwordx2 v[236:237], v164, s[20:21] offset:64
	global_load_dwordx2 v[238:239], v164, s[20:21] offset:96
	v_add_u32_e32 v164, 0x8000, v164
	global_load_dwordx2 v[240:241], v164, s[20:21] offset:0
	global_load_dwordx2 v[242:243], v164, s[20:21] offset:32
	global_load_dwordx2 v[244:245], v164, s[20:21] offset:64
	global_load_dwordx2 v[246:247], v164, s[20:21] offset:96
	v_add_u32_e32 v164, 0x8000, v164
	global_load_dwordx2 v[248:249], v164, s[20:21] offset:0
	global_load_dwordx2 v[250:251], v164, s[20:21] offset:32
	global_load_dwordx2 v[156:157], v164, s[20:21] offset:64
	global_load_dwordx2 v[158:159], v164, s[20:21] offset:96
	v_subrev_u32_e32 v164, 0x18000, v164
	s_waitcnt vmcnt(0)
; DI u32x4 pack8(const float (&v)[8]) { u32x4 r = {pk2(v[0], v[1]), pk2(v[2], v[3]), pk2(v[4], v[5]), pk2(v[6], v[7])}; return r; }
; DI void tile_outproj(const Params& p, int l, const Chunk& ck, int tile, int next, PF& pf, char* smem) {
;     ...
;   const int row = tid >> 1, half = tid & 1; float ssq = 0.f;
;   u16* xb = (u16*)(p.ws + OFF_XB) + (size_t)(m0 + row) * 1024 + n0 + half * 64;
; #pragma unroll
;   for (int c8 = 0; c8 < 8; ++c8) {
;     float v[8], x[8]; cs_ld8(Cs, row, half * 64 + c8 * 8, v); unpack8(*(const u32x4*)(xb + c8 * 8), x);
; #pragma unroll
;     for (int j = 0; j < 8; ++j) { v[j] += x[j]; ssq += v[j] * v[j]; }
;     *(u32x4*)(xb + c8 * 8) = pack8(v);
;   }
;   ((float*)(p.ws + OFF_PSMID))[(size_t)(m0 + row) * 16 + ni * 2 + half] = ssq;
	v_mov_b32_e32 v171, 0
	v_lshlrev_b32_e32 v167, 16, v224
	v_and_b32_e32 v168, 0xffff0000, v224
	v_lshlrev_b32_e32 v169, 16, v225
	v_and_b32_e32 v170, 0xffff0000, v225
	v_add_f32_e32 v2, v2, v167
	v_add_f32_e32 v3, v3, v168
	v_add_f32_e32 v4, v4, v169
	v_add_f32_e32 v5, v5, v170
	v_fma_f32 v171, v2, v2, v171
	v_fma_f32 v171, v3, v3, v171
	v_fma_f32 v171, v4, v4, v171
	v_fma_f32 v171, v5, v5, v171
	v_cvt_pk_bf16_f32 v2, v2, v3
	v_cvt_pk_bf16_f32 v3, v4, v5
	global_store_dwordx2 v164, v[2:3], s[20:21]
	v_lshlrev_b32_e32 v167, 16, v226
	v_and_b32_e32 v168, 0xffff0000, v226
	v_lshlrev_b32_e32 v169, 16, v227
	v_and_b32_e32 v170, 0xffff0000, v227
	v_add_f32_e32 v6, v6, v167
	v_add_f32_e32 v7, v7, v168
	v_add_f32_e32 v8, v8, v169
	v_add_f32_e32 v9, v9, v170
	v_fma_f32 v171, v6, v6, v171
	v_fma_f32 v171, v7, v7, v171
	v_fma_f32 v171, v8, v8, v171
	v_fma_f32 v171, v9, v9, v171
	v_cvt_pk_bf16_f32 v6, v6, v7
	v_cvt_pk_bf16_f32 v7, v8, v9
	global_store_dwordx2 v164, v[6:7], s[20:21] offset:32
	v_lshlrev_b32_e32 v167, 16, v228
	v_and_b32_e32 v168, 0xffff0000, v228
	v_lshlrev_b32_e32 v169, 16, v229
	v_and_b32_e32 v170, 0xffff0000, v229
	v_add_f32_e32 v10, v10, v167
	v_add_f32_e32 v11, v11, v168
	v_add_f32_e32 v12, v12, v169
	v_add_f32_e32 v13, v13, v170
	v_fma_f32 v171, v10, v10, v171
	v_fma_f32 v171, v11, v11, v171
	v_fma_f32 v171, v12, v12, v171
	v_fma_f32 v171, v13, v13, v171
	v_cvt_pk_bf16_f32 v10, v10, v11
	v_cvt_pk_bf16_f32 v11, v12, v13
	global_store_dwordx2 v164, v[10:11], s[20:21] offset:64
	v_lshlrev_b32_e32 v167, 16, v230
	v_and_b32_e32 v168, 0xffff0000, v230
	v_lshlrev_b32_e32 v169, 16, v231
	v_and_b32_e32 v170, 0xffff0000, v231
	v_add_f32_e32 v14, v14, v167
	v_add_f32_e32 v15, v15, v168
	v_add_f32_e32 v16, v16, v169
	v_add_f32_e32 v17, v17, v170
	v_fma_f32 v171, v14, v14, v171
	v_fma_f32 v171, v15, v15, v171
	v_fma_f32 v171, v16, v16, v171
	v_fma_f32 v171, v17, v17, v171
	v_cvt_pk_bf16_f32 v14, v14, v15
	v_cvt_pk_bf16_f32 v15, v16, v17
	global_store_dwordx2 v164, v[14:15], s[20:21] offset:96
	v_mov_b32_e32 v167, v171
	s_nop 1
	v_permlane32_swap_b32_e32 v171, v167
	v_add_f32_e32 v171, v171, v167
	ds_swizzle_b32 v167, v171 offset:0x401f
	s_waitcnt lgkmcnt(0)
	v_add_f32_e32 v171, v171, v167
	v_cmp_gt_u32_e32 vcc, 16, v160
	s_and_saveexec_b64 s[98:99], vcc
	global_store_dword v166, v171, s[14:15] offset:0
	s_or_b64 exec, exec, s[98:99]
	v_add_u32_e32 v164, 0x8000, v164
	v_mov_b32_e32 v171, 0
	v_lshlrev_b32_e32 v167, 16, v232
	v_and_b32_e32 v168, 0xffff0000, v232
	v_lshlrev_b32_e32 v169, 16, v233
	v_and_b32_e32 v170, 0xffff0000, v233
	v_add_f32_e32 v18, v18, v167
	v_add_f32_e32 v19, v19, v168
	v_add_f32_e32 v20, v20, v169
	v_add_f32_e32 v21, v21, v170
	v_fma_f32 v171, v18, v18, v171
	v_fma_f32 v171, v19, v19, v171
	v_fma_f32 v171, v20, v20, v171
	v_fma_f32 v171, v21, v21, v171
	v_cvt_pk_bf16_f32 v18, v18, v19
	v_cvt_pk_bf16_f32 v19, v20, v21
	global_store_dwordx2 v164, v[18:19], s[20:21]
	v_lshlrev_b32_e32 v167, 16, v234
	v_and_b32_e32 v168, 0xffff0000, v234
	v_lshlrev_b32_e32 v169, 16, v235
	v_and_b32_e32 v170, 0xffff0000, v235
	v_add_f32_e32 v22, v22, v167
	v_add_f32_e32 v23, v23, v168
	v_add_f32_e32 v24, v24, v169
	v_add_f32_e32 v25, v25, v170
	v_fma_f32 v171, v22, v22, v171
	v_fma_f32 v171, v23, v23, v171
	v_fma_f32 v171, v24, v24, v171
	v_fma_f32 v171, v25, v25, v171
	v_cvt_pk_bf16_f32 v22, v22, v23
	v_cvt_pk_bf16_f32 v23, v24, v25
	global_store_dwordx2 v164, v[22:23], s[20:21] offset:32
	v_lshlrev_b32_e32 v167, 16, v236
	v_and_b32_e32 v168, 0xffff0000, v236
	v_lshlrev_b32_e32 v169, 16, v237
	v_and_b32_e32 v170, 0xffff0000, v237
	v_add_f32_e32 v26, v26, v167
	v_add_f32_e32 v27, v27, v168
	v_add_f32_e32 v28, v28, v169
	v_add_f32_e32 v29, v29, v170
	v_fma_f32 v171, v26, v26, v171
	v_fma_f32 v171, v27, v27, v171
	v_fma_f32 v171, v28, v28, v171
	v_fma_f32 v171, v29, v29, v171
	v_cvt_pk_bf16_f32 v26, v26, v27
	v_cvt_pk_bf16_f32 v27, v28, v29
	global_store_dwordx2 v164, v[26:27], s[20:21] offset:64
	v_lshlrev_b32_e32 v167, 16, v238
	v_and_b32_e32 v168, 0xffff0000, v238
	v_lshlrev_b32_e32 v169, 16, v239
	v_and_b32_e32 v170, 0xffff0000, v239
	v_add_f32_e32 v30, v30, v167
	v_add_f32_e32 v31, v31, v168
	v_add_f32_e32 v32, v32, v169
	v_add_f32_e32 v33, v33, v170
	v_fma_f32 v171, v30, v30, v171
	v_fma_f32 v171, v31, v31, v171
	v_fma_f32 v171, v32, v32, v171
	v_fma_f32 v171, v33, v33, v171
	v_cvt_pk_bf16_f32 v30, v30, v31
	v_cvt_pk_bf16_f32 v31, v32, v33
	global_store_dwordx2 v164, v[30:31], s[20:21] offset:96
	v_mov_b32_e32 v167, v171
	s_nop 1
	v_permlane32_swap_b32_e32 v171, v167
	v_add_f32_e32 v171, v171, v167
	ds_swizzle_b32 v167, v171 offset:0x401f
	s_waitcnt lgkmcnt(0)
; DI u32x4 pack8(const float (&v)[8]) { u32x4 r = {pk2(v[0], v[1]), pk2(v[2], v[3]), pk2(v[4], v[5]), pk2(v[6], v[7])}; return r; }
; DI void tile_outproj(const Params& p, int l, const Chunk& ck, int tile, int next, PF& pf, char* smem) {
;     ...
;   const int row = tid >> 1, half = tid & 1; float ssq = 0.f;
;   u16* xb = (u16*)(p.ws + OFF_XB) + (size_t)(m0 + row) * 1024 + n0 + half * 64;
; #pragma unroll
;   for (int c8 = 0; c8 < 8; ++c8) {
;     float v[8], x[8]; cs_ld8(Cs, row, half * 64 + c8 * 8, v); unpack8(*(const u32x4*)(xb + c8 * 8), x);
; #pragma unroll
;     for (int j = 0; j < 8; ++j) { v[j] += x[j]; ssq += v[j] * v[j]; }
;     *(u32x4*)(xb + c8 * 8) = pack8(v);
;   }
;   ((float*)(p.ws + OFF_PSMID))[(size_t)(m0 + row) * 16 + ni * 2 + half] = ssq;
	v_add_f32_e32 v171, v171, v167
	v_cmp_gt_u32_e32 vcc, 16, v160
	s_and_saveexec_b64 s[98:99], vcc
	global_store_dword v166, v171, s[14:15] offset:1024
	s_or_b64 exec, exec, s[98:99]
	v_add_u32_e32 v164, 0x8000, v164
	v_mov_b32_e32 v171, 0
	v_lshlrev_b32_e32 v167, 16, v240
	v_and_b32_e32 v168, 0xffff0000, v240
	v_lshlrev_b32_e32 v169, 16, v241
	v_and_b32_e32 v170, 0xffff0000, v241
	v_add_f32_e32 v34, v34, v167
	v_add_f32_e32 v35, v35, v168
	v_add_f32_e32 v36, v36, v169
	v_add_f32_e32 v37, v37, v170
	v_fma_f32 v171, v34, v34, v171
	v_fma_f32 v171, v35, v35, v171
	v_fma_f32 v171, v36, v36, v171
	v_fma_f32 v171, v37, v37, v171
	v_cvt_pk_bf16_f32 v34, v34, v35
	v_cvt_pk_bf16_f32 v35, v36, v37
	global_store_dwordx2 v164, v[34:35], s[20:21]
	v_lshlrev_b32_e32 v167, 16, v242
	v_and_b32_e32 v168, 0xffff0000, v242
	v_lshlrev_b32_e32 v169, 16, v243
	v_and_b32_e32 v170, 0xffff0000, v243
	v_add_f32_e32 v38, v38, v167
	v_add_f32_e32 v39, v39, v168
	v_add_f32_e32 v40, v40, v169
	v_add_f32_e32 v41, v41, v170
	v_fma_f32 v171, v38, v38, v171
	v_fma_f32 v171, v39, v39, v171
	v_fma_f32 v171, v40, v40, v171
	v_fma_f32 v171, v41, v41, v171
	v_cvt_pk_bf16_f32 v38, v38, v39
	v_cvt_pk_bf16_f32 v39, v40, v41
	global_store_dwordx2 v164, v[38:39], s[20:21] offset:32
	v_lshlrev_b32_e32 v167, 16, v244
	v_and_b32_e32 v168, 0xffff0000, v244
	v_lshlrev_b32_e32 v169, 16, v245
	v_and_b32_e32 v170, 0xffff0000, v245
	v_add_f32_e32 v42, v42, v167
	v_add_f32_e32 v43, v43, v168
	v_add_f32_e32 v44, v44, v169
	v_add_f32_e32 v45, v45, v170
	v_fma_f32 v171, v42, v42, v171
	v_fma_f32 v171, v43, v43, v171
	v_fma_f32 v171, v44, v44, v171
	v_fma_f32 v171, v45, v45, v171
	v_cvt_pk_bf16_f32 v42, v42, v43
	v_cvt_pk_bf16_f32 v43, v44, v45
	global_store_dwordx2 v164, v[42:43], s[20:21] offset:64
	v_lshlrev_b32_e32 v167, 16, v246
	v_and_b32_e32 v168, 0xffff0000, v246
	v_lshlrev_b32_e32 v169, 16, v247
	v_and_b32_e32 v170, 0xffff0000, v247
	v_add_f32_e32 v46, v46, v167
	v_add_f32_e32 v47, v47, v168
	v_add_f32_e32 v48, v48, v169
	v_add_f32_e32 v49, v49, v170
	v_fma_f32 v171, v46, v46, v171
	v_fma_f32 v171, v47, v47, v171
	v_fma_f32 v171, v48, v48, v171
	v_fma_f32 v171, v49, v49, v171
	v_cvt_pk_bf16_f32 v46, v46, v47
	v_cvt_pk_bf16_f32 v47, v48, v49
	global_store_dwordx2 v164, v[46:47], s[20:21] offset:96
	v_mov_b32_e32 v167, v171
	s_nop 1
	v_permlane32_swap_b32_e32 v171, v167
	v_add_f32_e32 v171, v171, v167
	ds_swizzle_b32 v167, v171 offset:0x401f
	s_waitcnt lgkmcnt(0)
	v_add_f32_e32 v171, v171, v167
	v_cmp_gt_u32_e32 vcc, 16, v160
	s_and_saveexec_b64 s[98:99], vcc
	global_store_dword v166, v171, s[14:15] offset:2048
	s_or_b64 exec, exec, s[98:99]
	v_add_u32_e32 v164, 0x8000, v164
	v_mov_b32_e32 v171, 0
	v_lshlrev_b32_e32 v167, 16, v248
	v_and_b32_e32 v168, 0xffff0000, v248
	v_lshlrev_b32_e32 v169, 16, v249
	v_and_b32_e32 v170, 0xffff0000, v249
	v_add_f32_e32 v50, v50, v167
	v_add_f32_e32 v51, v51, v168
	v_add_f32_e32 v52, v52, v169
	v_add_f32_e32 v53, v53, v170
	v_fma_f32 v171, v50, v50, v171
	v_fma_f32 v171, v51, v51, v171
	v_fma_f32 v171, v52, v52, v171
	v_fma_f32 v171, v53, v53, v171
	v_cvt_pk_bf16_f32 v50, v50, v51
	v_cvt_pk_bf16_f32 v51, v52, v53
	global_store_dwordx2 v164, v[50:51], s[20:21]
	v_lshlrev_b32_e32 v167, 16, v250
	v_and_b32_e32 v168, 0xffff0000, v250
	v_lshlrev_b32_e32 v169, 16, v251
	v_and_b32_e32 v170, 0xffff0000, v251
	v_add_f32_e32 v54, v54, v167
	v_add_f32_e32 v55, v55, v168
	v_add_f32_e32 v56, v56, v169
	v_add_f32_e32 v57, v57, v170
	v_fma_f32 v171, v54, v54, v171
	v_fma_f32 v171, v55, v55, v171
	v_fma_f32 v171, v56, v56, v171
	v_fma_f32 v171, v57, v57, v171
	v_cvt_pk_bf16_f32 v54, v54, v55
	v_cvt_pk_bf16_f32 v55, v56, v57
	global_store_dwordx2 v164, v[54:55], s[20:21] offset:32
	v_lshlrev_b32_e32 v167, 16, v156
	v_and_b32_e32 v168, 0xffff0000, v156
	v_lshlrev_b32_e32 v169, 16, v157
	v_and_b32_e32 v170, 0xffff0000, v157
	v_add_f32_e32 v58, v58, v167
	v_add_f32_e32 v59, v59, v168
	v_add_f32_e32 v60, v60, v169
	v_add_f32_e32 v61, v61, v170
	v_fma_f32 v171, v58, v58, v171
	v_fma_f32 v171, v59, v59, v171
	v_fma_f32 v171, v60, v60, v171
	v_fma_f32 v171, v61, v61, v171
	v_cvt_pk_bf16_f32 v58, v58, v59
	v_cvt_pk_bf16_f32 v59, v60, v61
	global_store_dwordx2 v164, v[58:59], s[20:21] offset:64
	v_lshlrev_b32_e32 v167, 16, v158
	v_and_b32_e32 v168, 0xffff0000, v158
	v_lshlrev_b32_e32 v169, 16, v159
	v_and_b32_e32 v170, 0xffff0000, v159
	v_add_f32_e32 v62, v62, v167
	v_add_f32_e32 v63, v63, v168
	v_add_f32_e32 v64, v64, v169
	v_add_f32_e32 v65, v65, v170
	v_fma_f32 v171, v62, v62, v171
	v_fma_f32 v171, v63, v63, v171
	v_fma_f32 v171, v64, v64, v171
	v_fma_f32 v171, v65, v65, v171
	v_cvt_pk_bf16_f32 v62, v62, v63
	v_cvt_pk_bf16_f32 v63, v64, v65
	global_store_dwordx2 v164, v[62:63], s[20:21] offset:96
	v_mov_b32_e32 v167, v171
	s_nop 1
	v_permlane32_swap_b32_e32 v171, v167
	v_add_f32_e32 v171, v171, v167
	ds_swizzle_b32 v167, v171 offset:0x401f
	s_waitcnt lgkmcnt(0)
	v_add_f32_e32 v171, v171, v167
	v_cmp_gt_u32_e32 vcc, 16, v160
	s_and_saveexec_b64 s[98:99], vcc
	global_store_dword v166, v171, s[14:15] offset:3072
	s_or_b64 exec, exec, s[98:99]
	v_subrev_u32_e32 v164, 0x18000, v164
	global_load_dwordx2 v[224:225], v164, s[20:21] offset:256
	global_load_dwordx2 v[226:227], v164, s[20:21] offset:288
	global_load_dwordx2 v[228:229], v164, s[20:21] offset:320
	global_load_dwordx2 v[230:231], v164, s[20:21] offset:352
	v_add_u32_e32 v164, 0x8000, v164
	global_load_dwordx2 v[232:233], v164, s[20:21] offset:256
	global_load_dwordx2 v[234:235], v164, s[20:21] offset:288
	global_load_dwordx2 v[236:237], v164, s[20:21] offset:320
	global_load_dwordx2 v[238:239], v164, s[20:21] offset:352
	v_add_u32_e32 v164, 0x8000, v164
	global_load_dwordx2 v[240:241], v164, s[20:21] offset:256
	global_load_dwordx2 v[242:243], v164, s[20:21] offset:288
	global_load_dwordx2 v[244:245], v164, s[20:21] offset:320
	global_load_dwordx2 v[246:247], v164, s[20:21] offset:352
	v_add_u32_e32 v164, 0x8000, v164
	global_load_dwordx2 v[248:249], v164, s[20:21] offset:256
	global_load_dwordx2 v[250:251], v164, s[20:21] offset:288
	global_load_dwordx2 v[156:157], v164, s[20:21] offset:320
	global_load_dwordx2 v[158:159], v164, s[20:21] offset:352
	v_subrev_u32_e32 v164, 0x18000, v164
	s_waitcnt vmcnt(0)
; DI u32x4 pack8(const float (&v)[8]) { u32x4 r = {pk2(v[0], v[1]), pk2(v[2], v[3]), pk2(v[4], v[5]), pk2(v[6], v[7])}; return r; }
; DI void tile_outproj(const Params& p, int l, const Chunk& ck, int tile, int next, PF& pf, char* smem) {
;     ...
;   const int row = tid >> 1, half = tid & 1; float ssq = 0.f;
;   u16* xb = (u16*)(p.ws + OFF_XB) + (size_t)(m0 + row) * 1024 + n0 + half * 64;
; #pragma unroll
;   for (int c8 = 0; c8 < 8; ++c8) {
;     float v[8], x[8]; cs_ld8(Cs, row, half * 64 + c8 * 8, v); unpack8(*(const u32x4*)(xb + c8 * 8), x);
; #pragma unroll
;     for (int j = 0; j < 8; ++j) { v[j] += x[j]; ssq += v[j] * v[j]; }
;     *(u32x4*)(xb + c8 * 8) = pack8(v);
;   }
;   ((float*)(p.ws + OFF_PSMID))[(size_t)(m0 + row) * 16 + ni * 2 + half] = ssq;
	v_mov_b32_e32 v171, 0
	v_lshlrev_b32_e32 v167, 16, v224
	v_and_b32_e32 v168, 0xffff0000, v224
	v_lshlrev_b32_e32 v169, 16, v225
	v_and_b32_e32 v170, 0xffff0000, v225
	v_add_f32_e32 v74, v74, v167
	v_add_f32_e32 v75, v75, v168
	v_add_f32_e32 v76, v76, v169
	v_add_f32_e32 v77, v77, v170
	v_fma_f32 v171, v74, v74, v171
	v_fma_f32 v171, v75, v75, v171
	v_fma_f32 v171, v76, v76, v171
	v_fma_f32 v171, v77, v77, v171
	v_cvt_pk_bf16_f32 v74, v74, v75
	v_cvt_pk_bf16_f32 v75, v76, v77
	global_store_dwordx2 v164, v[74:75], s[20:21] offset:256
	v_lshlrev_b32_e32 v167, 16, v226
	v_and_b32_e32 v168, 0xffff0000, v226
	v_lshlrev_b32_e32 v169, 16, v227
	v_and_b32_e32 v170, 0xffff0000, v227
	v_add_f32_e32 v78, v78, v167
	v_add_f32_e32 v79, v79, v168
	v_add_f32_e32 v80, v80, v169
	v_add_f32_e32 v81, v81, v170
	v_fma_f32 v171, v78, v78, v171
	v_fma_f32 v171, v79, v79, v171
	v_fma_f32 v171, v80, v80, v171
	v_fma_f32 v171, v81, v81, v171
	v_cvt_pk_bf16_f32 v78, v78, v79
	v_cvt_pk_bf16_f32 v79, v80, v81
	global_store_dwordx2 v164, v[78:79], s[20:21] offset:288
	v_lshlrev_b32_e32 v167, 16, v228
	v_and_b32_e32 v168, 0xffff0000, v228
	v_lshlrev_b32_e32 v169, 16, v229
	v_and_b32_e32 v170, 0xffff0000, v229
	v_add_f32_e32 v82, v82, v167
	v_add_f32_e32 v83, v83, v168
	v_add_f32_e32 v84, v84, v169
	v_add_f32_e32 v85, v85, v170
	v_fma_f32 v171, v82, v82, v171
	v_fma_f32 v171, v83, v83, v171
	v_fma_f32 v171, v84, v84, v171
	v_fma_f32 v171, v85, v85, v171
	v_cvt_pk_bf16_f32 v82, v82, v83
	v_cvt_pk_bf16_f32 v83, v84, v85
	global_store_dwordx2 v164, v[82:83], s[20:21] offset:320
	v_lshlrev_b32_e32 v167, 16, v230
	v_and_b32_e32 v168, 0xffff0000, v230
	v_lshlrev_b32_e32 v169, 16, v231
	v_and_b32_e32 v170, 0xffff0000, v231
	v_add_f32_e32 v86, v86, v167
	v_add_f32_e32 v87, v87, v168
	v_add_f32_e32 v88, v88, v169
	v_add_f32_e32 v89, v89, v170
	v_fma_f32 v171, v86, v86, v171
	v_fma_f32 v171, v87, v87, v171
	v_fma_f32 v171, v88, v88, v171
	v_fma_f32 v171, v89, v89, v171
	v_cvt_pk_bf16_f32 v86, v86, v87
	v_cvt_pk_bf16_f32 v87, v88, v89
	global_store_dwordx2 v164, v[86:87], s[20:21] offset:352
	v_mov_b32_e32 v167, v171
	s_nop 1
	v_permlane32_swap_b32_e32 v171, v167
	v_add_f32_e32 v171, v171, v167
	ds_swizzle_b32 v167, v171 offset:0x401f
	s_waitcnt lgkmcnt(0)
	v_add_f32_e32 v171, v171, v167
	v_cmp_gt_u32_e32 vcc, 16, v160
	s_and_saveexec_b64 s[98:99], vcc
	global_store_dword v166, v171, s[14:15] offset:8
	s_or_b64 exec, exec, s[98:99]
	v_add_u32_e32 v164, 0x8000, v164
	v_mov_b32_e32 v171, 0
	v_lshlrev_b32_e32 v167, 16, v232
	v_and_b32_e32 v168, 0xffff0000, v232
	v_lshlrev_b32_e32 v169, 16, v233
	v_and_b32_e32 v170, 0xffff0000, v233
	v_add_f32_e32 v90, v90, v167
	v_add_f32_e32 v91, v91, v168
	v_add_f32_e32 v92, v92, v169
	v_add_f32_e32 v93, v93, v170
	v_fma_f32 v171, v90, v90, v171
	v_fma_f32 v171, v91, v91, v171
	v_fma_f32 v171, v92, v92, v171
	v_fma_f32 v171, v93, v93, v171
	v_cvt_pk_bf16_f32 v90, v90, v91
	v_cvt_pk_bf16_f32 v91, v92, v93
	global_store_dwordx2 v164, v[90:91], s[20:21] offset:256
	v_lshlrev_b32_e32 v167, 16, v234
	v_and_b32_e32 v168, 0xffff0000, v234
	v_lshlrev_b32_e32 v169, 16, v235
	v_and_b32_e32 v170, 0xffff0000, v235
	v_add_f32_e32 v94, v94, v167
	v_add_f32_e32 v95, v95, v168
	v_add_f32_e32 v96, v96, v169
	v_add_f32_e32 v97, v97, v170
	v_fma_f32 v171, v94, v94, v171
	v_fma_f32 v171, v95, v95, v171
	v_fma_f32 v171, v96, v96, v171
	v_fma_f32 v171, v97, v97, v171
	v_cvt_pk_bf16_f32 v94, v94, v95
	v_cvt_pk_bf16_f32 v95, v96, v97
	global_store_dwordx2 v164, v[94:95], s[20:21] offset:288
	v_lshlrev_b32_e32 v167, 16, v236
	v_and_b32_e32 v168, 0xffff0000, v236
	v_lshlrev_b32_e32 v169, 16, v237
	v_and_b32_e32 v170, 0xffff0000, v237
	v_add_f32_e32 v98, v98, v167
	v_add_f32_e32 v99, v99, v168
	v_add_f32_e32 v100, v100, v169
	v_add_f32_e32 v101, v101, v170
	v_fma_f32 v171, v98, v98, v171
	v_fma_f32 v171, v99, v99, v171
	v_fma_f32 v171, v100, v100, v171
	v_fma_f32 v171, v101, v101, v171
	v_cvt_pk_bf16_f32 v98, v98, v99
	v_cvt_pk_bf16_f32 v99, v100, v101
	global_store_dwordx2 v164, v[98:99], s[20:21] offset:320
	v_lshlrev_b32_e32 v167, 16, v238
	v_and_b32_e32 v168, 0xffff0000, v238
	v_lshlrev_b32_e32 v169, 16, v239
	v_and_b32_e32 v170, 0xffff0000, v239
	v_add_f32_e32 v102, v102, v167
	v_add_f32_e32 v103, v103, v168
	v_add_f32_e32 v104, v104, v169
	v_add_f32_e32 v105, v105, v170
	v_fma_f32 v171, v102, v102, v171
	v_fma_f32 v171, v103, v103, v171
	v_fma_f32 v171, v104, v104, v171
	v_fma_f32 v171, v105, v105, v171
	v_cvt_pk_bf16_f32 v102, v102, v103
	v_cvt_pk_bf16_f32 v103, v104, v105
	global_store_dwordx2 v164, v[102:103], s[20:21] offset:352
	v_mov_b32_e32 v167, v171
	s_nop 1
	v_permlane32_swap_b32_e32 v171, v167
	v_add_f32_e32 v171, v171, v167
	ds_swizzle_b32 v167, v171 offset:0x401f
	s_waitcnt lgkmcnt(0)
; DI u32x4 pack8(const float (&v)[8]) { u32x4 r = {pk2(v[0], v[1]), pk2(v[2], v[3]), pk2(v[4], v[5]), pk2(v[6], v[7])}; return r; }
; DI void tile_outproj(const Params& p, int l, const Chunk& ck, int tile, int next, PF& pf, char* smem) {
;     ...
;   const int row = tid >> 1, half = tid & 1; float ssq = 0.f;
;   u16* xb = (u16*)(p.ws + OFF_XB) + (size_t)(m0 + row) * 1024 + n0 + half * 64;
; #pragma unroll
;   for (int c8 = 0; c8 < 8; ++c8) {
;     float v[8], x[8]; cs_ld8(Cs, row, half * 64 + c8 * 8, v); unpack8(*(const u32x4*)(xb + c8 * 8), x);
; #pragma unroll
;     for (int j = 0; j < 8; ++j) { v[j] += x[j]; ssq += v[j] * v[j]; }
;     *(u32x4*)(xb + c8 * 8) = pack8(v);
;   }
;   ((float*)(p.ws + OFF_PSMID))[(size_t)(m0 + row) * 16 + ni * 2 + half] = ssq;
	v_add_f32_e32 v171, v171, v167
	v_cmp_gt_u32_e32 vcc, 16, v160
	s_and_saveexec_b64 s[98:99], vcc
	global_store_dword v166, v171, s[14:15] offset:1032
	s_or_b64 exec, exec, s[98:99]
	v_add_u32_e32 v164, 0x8000, v164
	v_mov_b32_e32 v171, 0
	v_lshlrev_b32_e32 v167, 16, v240
	v_and_b32_e32 v168, 0xffff0000, v240
	v_lshlrev_b32_e32 v169, 16, v241
	v_and_b32_e32 v170, 0xffff0000, v241
	v_add_f32_e32 v106, v106, v167
	v_add_f32_e32 v107, v107, v168
	v_add_f32_e32 v108, v108, v169
	v_add_f32_e32 v109, v109, v170
	v_fma_f32 v171, v106, v106, v171
	v_fma_f32 v171, v107, v107, v171
	v_fma_f32 v171, v108, v108, v171
	v_fma_f32 v171, v109, v109, v171
	v_cvt_pk_bf16_f32 v106, v106, v107
	v_cvt_pk_bf16_f32 v107, v108, v109
	global_store_dwordx2 v164, v[106:107], s[20:21] offset:256
	v_lshlrev_b32_e32 v167, 16, v242
	v_and_b32_e32 v168, 0xffff0000, v242
	v_lshlrev_b32_e32 v169, 16, v243
	v_and_b32_e32 v170, 0xffff0000, v243
	v_add_f32_e32 v110, v110, v167
	v_add_f32_e32 v111, v111, v168
	v_add_f32_e32 v112, v112, v169
	v_add_f32_e32 v113, v113, v170
	v_fma_f32 v171, v110, v110, v171
	v_fma_f32 v171, v111, v111, v171
	v_fma_f32 v171, v112, v112, v171
	v_fma_f32 v171, v113, v113, v171
	v_cvt_pk_bf16_f32 v110, v110, v111
	v_cvt_pk_bf16_f32 v111, v112, v113
	global_store_dwordx2 v164, v[110:111], s[20:21] offset:288
	v_lshlrev_b32_e32 v167, 16, v244
	v_and_b32_e32 v168, 0xffff0000, v244
	v_lshlrev_b32_e32 v169, 16, v245
	v_and_b32_e32 v170, 0xffff0000, v245
	v_add_f32_e32 v114, v114, v167
	v_add_f32_e32 v115, v115, v168
	v_add_f32_e32 v116, v116, v169
	v_add_f32_e32 v117, v117, v170
	v_fma_f32 v171, v114, v114, v171
	v_fma_f32 v171, v115, v115, v171
	v_fma_f32 v171, v116, v116, v171
	v_fma_f32 v171, v117, v117, v171
	v_cvt_pk_bf16_f32 v114, v114, v115
	v_cvt_pk_bf16_f32 v115, v116, v117
	global_store_dwordx2 v164, v[114:115], s[20:21] offset:320
	v_lshlrev_b32_e32 v167, 16, v246
	v_and_b32_e32 v168, 0xffff0000, v246
	v_lshlrev_b32_e32 v169, 16, v247
	v_and_b32_e32 v170, 0xffff0000, v247
	v_add_f32_e32 v118, v118, v167
	v_add_f32_e32 v119, v119, v168
	v_add_f32_e32 v120, v120, v169
	v_add_f32_e32 v121, v121, v170
	v_fma_f32 v171, v118, v118, v171
	v_fma_f32 v171, v119, v119, v171
	v_fma_f32 v171, v120, v120, v171
	v_fma_f32 v171, v121, v121, v171
	v_cvt_pk_bf16_f32 v118, v118, v119
	v_cvt_pk_bf16_f32 v119, v120, v121
	global_store_dwordx2 v164, v[118:119], s[20:21] offset:352
	v_mov_b32_e32 v167, v171
	s_nop 1
	v_permlane32_swap_b32_e32 v171, v167
	v_add_f32_e32 v171, v171, v167
	ds_swizzle_b32 v167, v171 offset:0x401f
	s_waitcnt lgkmcnt(0)
	v_add_f32_e32 v171, v171, v167
	v_cmp_gt_u32_e32 vcc, 16, v160
	s_and_saveexec_b64 s[98:99], vcc
	global_store_dword v166, v171, s[14:15] offset:2056
	s_or_b64 exec, exec, s[98:99]
	v_add_u32_e32 v164, 0x8000, v164
	v_mov_b32_e32 v171, 0
	v_lshlrev_b32_e32 v167, 16, v248
	v_and_b32_e32 v168, 0xffff0000, v248
	v_lshlrev_b32_e32 v169, 16, v249
	v_and_b32_e32 v170, 0xffff0000, v249
	v_add_f32_e32 v208, v208, v167
	v_add_f32_e32 v209, v209, v168
	v_add_f32_e32 v210, v210, v169
	v_add_f32_e32 v211, v211, v170
	v_fma_f32 v171, v208, v208, v171
	v_fma_f32 v171, v209, v209, v171
	v_fma_f32 v171, v210, v210, v171
	v_fma_f32 v171, v211, v211, v171
	v_cvt_pk_bf16_f32 v208, v208, v209
	v_cvt_pk_bf16_f32 v209, v210, v211
	global_store_dwordx2 v164, v[208:209], s[20:21] offset:256
	v_lshlrev_b32_e32 v167, 16, v250
	v_and_b32_e32 v168, 0xffff0000, v250
	v_lshlrev_b32_e32 v169, 16, v251
	v_and_b32_e32 v170, 0xffff0000, v251
	v_add_f32_e32 v212, v212, v167
	v_add_f32_e32 v213, v213, v168
	v_add_f32_e32 v214, v214, v169
	v_add_f32_e32 v215, v215, v170
	v_fma_f32 v171, v212, v212, v171
	v_fma_f32 v171, v213, v213, v171
	v_fma_f32 v171, v214, v214, v171
	v_fma_f32 v171, v215, v215, v171
	v_cvt_pk_bf16_f32 v212, v212, v213
	v_cvt_pk_bf16_f32 v213, v214, v215
	global_store_dwordx2 v164, v[212:213], s[20:21] offset:288
	v_lshlrev_b32_e32 v167, 16, v156
	v_and_b32_e32 v168, 0xffff0000, v156
	v_lshlrev_b32_e32 v169, 16, v157
	v_and_b32_e32 v170, 0xffff0000, v157
	v_add_f32_e32 v216, v216, v167
	v_add_f32_e32 v217, v217, v168
	v_add_f32_e32 v218, v218, v169
	v_add_f32_e32 v219, v219, v170
	v_fma_f32 v171, v216, v216, v171
	v_fma_f32 v171, v217, v217, v171
	v_fma_f32 v171, v218, v218, v171
	v_fma_f32 v171, v219, v219, v171
	v_cvt_pk_bf16_f32 v216, v216, v217
	v_cvt_pk_bf16_f32 v217, v218, v219
	global_store_dwordx2 v164, v[216:217], s[20:21] offset:320
	v_lshlrev_b32_e32 v167, 16, v158
	v_and_b32_e32 v168, 0xffff0000, v158
	v_lshlrev_b32_e32 v169, 16, v159
	v_and_b32_e32 v170, 0xffff0000, v159
	v_add_f32_e32 v220, v220, v167
	v_add_f32_e32 v221, v221, v168
	v_add_f32_e32 v222, v222, v169
	v_add_f32_e32 v223, v223, v170
	v_fma_f32 v171, v220, v220, v171
	v_fma_f32 v171, v221, v221, v171
	v_fma_f32 v171, v222, v222, v171
	v_fma_f32 v171, v223, v223, v171
	v_cvt_pk_bf16_f32 v220, v220, v221
	v_cvt_pk_bf16_f32 v221, v222, v223
	global_store_dwordx2 v164, v[220:221], s[20:21] offset:352
	v_mov_b32_e32 v167, v171
	s_nop 1
	v_permlane32_swap_b32_e32 v171, v167
	v_add_f32_e32 v171, v171, v167
	ds_swizzle_b32 v167, v171 offset:0x401f
	s_waitcnt lgkmcnt(0)
	v_add_f32_e32 v171, v171, v167
	v_cmp_gt_u32_e32 vcc, 16, v160
	s_and_saveexec_b64 s[98:99], vcc
	global_store_dword v166, v171, s[14:15] offset:3080
	s_or_b64 exec, exec, s[98:99]
	v_subrev_u32_e32 v164, 0x18000, v164
	s_branch .LBB1_254
